# conv LayerNorm: the two wave reductions of the 4 tokens of a wave run side by side (12 LDS round trips per tile instead of 48)
# baseline (speedup 1.0000x reference)
.LBB0_696:
	v_or_b32_e32 v47, s2, v91
	v_cndmask_b32_e64 v46, 0, 1, s[10:11]
	v_lshl_add_u32 v103, v47, 10, v92
	v_cmp_ne_u32_e32 vcc, 1, v46
	ds_read2st64_b32 v[46:47], v103 offset1:4
	ds_read2st64_b32 v[48:49], v103 offset0:8 offset1:12
	ds_read2st64_b32 v[50:51], v103 offset0:16 offset1:20
	ds_read2st64_b32 v[52:53], v103 offset0:24 offset1:28
	ds_read2st64_b32 v[104:105], v103 offset0:32 offset1:36
	ds_read2st64_b32 v[106:107], v103 offset0:40 offset1:44
	ds_read2st64_b32 v[108:109], v103 offset0:48 offset1:52
	ds_read2st64_b32 v[110:111], v103 offset0:56 offset1:60
	ds_read2st64_b32 v[112:113], v103 offset0:64 offset1:68
	ds_read2st64_b32 v[114:115], v103 offset0:72 offset1:76
	ds_read2st64_b32 v[116:117], v103 offset0:80 offset1:84
	ds_read2st64_b32 v[118:119], v103 offset0:88 offset1:92
	ds_read2st64_b32 v[120:121], v103 offset0:96 offset1:100
	ds_read2st64_b32 v[122:123], v103 offset0:104 offset1:108
	ds_read2st64_b32 v[124:125], v103 offset0:112 offset1:116
	ds_read2st64_b32 v[126:127], v103 offset0:120 offset1:124
	ds_read2st64_b32 v[128:129], v103 offset0:128 offset1:132
	ds_read2st64_b32 v[130:131], v103 offset0:136 offset1:140
	ds_read2st64_b32 v[132:133], v103 offset0:144 offset1:148
	s_waitcnt lgkmcnt(14)
	v_fma_f32 v46, v59, v46, v90
	v_fma_f32 v140, v59, v47, v90
	v_fma_f32 v141, v59, v48, v90
	v_fma_f32 v142, v59, v49, v90
	v_fma_f32 v143, v59, v50, v90
	v_fma_f32 v144, v59, v51, v90
	v_fma_f32 v145, v59, v52, v90
	v_fma_f32 v146, v59, v53, v90
	v_fmac_f32_e32 v46, v60, v47
	v_fmac_f32_e32 v140, v60, v48
	v_fmac_f32_e32 v141, v60, v49
	v_fmac_f32_e32 v142, v60, v50
	v_fmac_f32_e32 v143, v60, v51
	v_fmac_f32_e32 v144, v60, v52
	v_fmac_f32_e32 v145, v60, v53
	v_fmac_f32_e32 v146, v60, v104
	v_fmac_f32_e32 v46, v61, v48
	v_fmac_f32_e32 v140, v61, v49
	v_fmac_f32_e32 v141, v61, v50
	v_fmac_f32_e32 v142, v61, v51
	v_fmac_f32_e32 v143, v61, v52
	v_fmac_f32_e32 v144, v61, v53
	v_fmac_f32_e32 v145, v61, v104
	v_fmac_f32_e32 v146, v61, v105
	v_fmac_f32_e32 v46, v62, v49
	v_fmac_f32_e32 v140, v62, v50
	v_fmac_f32_e32 v141, v62, v51
	v_fmac_f32_e32 v142, v62, v52
	v_fmac_f32_e32 v143, v62, v53
	v_fmac_f32_e32 v144, v62, v104
	v_fmac_f32_e32 v145, v62, v105
	s_waitcnt lgkmcnt(13)
	v_fmac_f32_e32 v146, v62, v106
	v_fmac_f32_e32 v46, v63, v50
	v_fmac_f32_e32 v140, v63, v51
	v_fmac_f32_e32 v141, v63, v52
	v_fmac_f32_e32 v142, v63, v53
	v_fmac_f32_e32 v143, v63, v104
	v_fmac_f32_e32 v144, v63, v105
	v_fmac_f32_e32 v145, v63, v106
	v_fmac_f32_e32 v146, v63, v107
	v_fmac_f32_e32 v46, v64, v51
	v_fmac_f32_e32 v140, v64, v52
	v_fmac_f32_e32 v141, v64, v53
	v_fmac_f32_e32 v142, v64, v104
	v_fmac_f32_e32 v143, v64, v105
	v_fmac_f32_e32 v144, v64, v106
	v_fmac_f32_e32 v145, v64, v107
	s_waitcnt lgkmcnt(12)
	v_fmac_f32_e32 v146, v64, v108
	v_fmac_f32_e32 v46, v65, v52
	v_fmac_f32_e32 v140, v65, v53
	v_fmac_f32_e32 v141, v65, v104
	v_fmac_f32_e32 v142, v65, v105
	v_fmac_f32_e32 v143, v65, v106
	v_fmac_f32_e32 v144, v65, v107
	v_fmac_f32_e32 v145, v65, v108
	v_fmac_f32_e32 v146, v65, v109
	v_fmac_f32_e32 v46, v66, v53
	v_fmac_f32_e32 v140, v66, v104
	v_fmac_f32_e32 v141, v66, v105
	v_fmac_f32_e32 v142, v66, v106
	v_fmac_f32_e32 v143, v66, v107
	v_fmac_f32_e32 v144, v66, v108
	v_fmac_f32_e32 v145, v66, v109
	s_waitcnt lgkmcnt(11)
	v_fmac_f32_e32 v146, v66, v110
	v_fmac_f32_e32 v46, v67, v104
	v_fmac_f32_e32 v140, v67, v105
	v_fmac_f32_e32 v141, v67, v106
	v_fmac_f32_e32 v142, v67, v107
	v_fmac_f32_e32 v143, v67, v108
	v_fmac_f32_e32 v144, v67, v109
	v_fmac_f32_e32 v145, v67, v110
	v_fmac_f32_e32 v146, v67, v111
	v_fmac_f32_e32 v46, v68, v105
	v_fmac_f32_e32 v140, v68, v106
	v_fmac_f32_e32 v141, v68, v107
	v_fmac_f32_e32 v142, v68, v108
	v_fmac_f32_e32 v143, v68, v109
	v_fmac_f32_e32 v144, v68, v110
	v_fmac_f32_e32 v145, v68, v111
	s_waitcnt lgkmcnt(10)
	v_fmac_f32_e32 v146, v68, v112
	v_fmac_f32_e32 v46, v69, v106
	v_fmac_f32_e32 v140, v69, v107
	v_fmac_f32_e32 v141, v69, v108
	v_fmac_f32_e32 v142, v69, v109
	v_fmac_f32_e32 v143, v69, v110
	v_fmac_f32_e32 v144, v69, v111
	v_fmac_f32_e32 v145, v69, v112
	v_fmac_f32_e32 v146, v69, v113
	v_fmac_f32_e32 v46, v70, v107
	v_fmac_f32_e32 v140, v70, v108
	v_fmac_f32_e32 v141, v70, v109
	v_fmac_f32_e32 v142, v70, v110
	v_fmac_f32_e32 v143, v70, v111
	v_fmac_f32_e32 v144, v70, v112
	v_fmac_f32_e32 v145, v70, v113
	s_waitcnt lgkmcnt(9)
	v_fmac_f32_e32 v146, v70, v114
	v_fmac_f32_e32 v46, v71, v108
	v_fmac_f32_e32 v140, v71, v109
	v_fmac_f32_e32 v141, v71, v110
	v_fmac_f32_e32 v142, v71, v111
	v_fmac_f32_e32 v143, v71, v112
	v_fmac_f32_e32 v144, v71, v113
	v_fmac_f32_e32 v145, v71, v114
	v_fmac_f32_e32 v146, v71, v115
	v_fmac_f32_e32 v46, v72, v109
	v_fmac_f32_e32 v140, v72, v110
	v_fmac_f32_e32 v141, v72, v111
	v_fmac_f32_e32 v142, v72, v112
	v_fmac_f32_e32 v143, v72, v113
	v_fmac_f32_e32 v144, v72, v114
	v_fmac_f32_e32 v145, v72, v115
	s_waitcnt lgkmcnt(8)
	v_fmac_f32_e32 v146, v72, v116
	v_fmac_f32_e32 v46, v73, v110
	v_fmac_f32_e32 v140, v73, v111
	v_fmac_f32_e32 v141, v73, v112
	v_fmac_f32_e32 v142, v73, v113
	v_fmac_f32_e32 v143, v73, v114
	v_fmac_f32_e32 v144, v73, v115
	v_fmac_f32_e32 v145, v73, v116
	v_fmac_f32_e32 v146, v73, v117
	v_fmac_f32_e32 v46, v74, v111
	v_fmac_f32_e32 v140, v74, v112
	v_fmac_f32_e32 v141, v74, v113
	v_fmac_f32_e32 v142, v74, v114
	v_fmac_f32_e32 v143, v74, v115
	v_fmac_f32_e32 v144, v74, v116
	v_fmac_f32_e32 v145, v74, v117
	s_waitcnt lgkmcnt(7)
	v_fmac_f32_e32 v146, v74, v118
	v_fmac_f32_e32 v46, v75, v112
	v_fmac_f32_e32 v140, v75, v113
	v_fmac_f32_e32 v141, v75, v114
	v_fmac_f32_e32 v142, v75, v115
	v_fmac_f32_e32 v143, v75, v116
	v_fmac_f32_e32 v144, v75, v117
	v_fmac_f32_e32 v145, v75, v118
	v_fmac_f32_e32 v146, v75, v119
	v_fmac_f32_e32 v46, v76, v113
	v_fmac_f32_e32 v140, v76, v114
	v_fmac_f32_e32 v141, v76, v115
	v_fmac_f32_e32 v142, v76, v116
	v_fmac_f32_e32 v143, v76, v117
	v_fmac_f32_e32 v144, v76, v118
	v_fmac_f32_e32 v145, v76, v119
	s_waitcnt lgkmcnt(6)
	v_fmac_f32_e32 v146, v76, v120
	v_fmac_f32_e32 v46, v77, v114
	v_fmac_f32_e32 v140, v77, v115
	v_fmac_f32_e32 v141, v77, v116
	v_fmac_f32_e32 v142, v77, v117
	v_fmac_f32_e32 v143, v77, v118
	v_fmac_f32_e32 v144, v77, v119
	v_fmac_f32_e32 v145, v77, v120
	v_fmac_f32_e32 v146, v77, v121
	v_fmac_f32_e32 v46, v78, v115
	v_fmac_f32_e32 v140, v78, v116
	v_fmac_f32_e32 v141, v78, v117
	v_fmac_f32_e32 v142, v78, v118
	v_fmac_f32_e32 v143, v78, v119
	v_fmac_f32_e32 v144, v78, v120
	v_fmac_f32_e32 v145, v78, v121
	s_waitcnt lgkmcnt(5)
	v_fmac_f32_e32 v146, v78, v122
	v_fmac_f32_e32 v46, v79, v116
	v_fmac_f32_e32 v140, v79, v117
	v_fmac_f32_e32 v141, v79, v118
	v_fmac_f32_e32 v142, v79, v119
	v_fmac_f32_e32 v143, v79, v120
	v_fmac_f32_e32 v144, v79, v121
	v_fmac_f32_e32 v145, v79, v122
	v_fmac_f32_e32 v146, v79, v123
	v_fmac_f32_e32 v46, v80, v117
	v_fmac_f32_e32 v140, v80, v118
	v_fmac_f32_e32 v141, v80, v119
	v_fmac_f32_e32 v142, v80, v120
	v_fmac_f32_e32 v143, v80, v121
	v_fmac_f32_e32 v144, v80, v122
	v_fmac_f32_e32 v145, v80, v123
	s_waitcnt lgkmcnt(4)
	v_fmac_f32_e32 v146, v80, v124
	v_fmac_f32_e32 v46, v81, v118
	v_fmac_f32_e32 v140, v81, v119
	v_fmac_f32_e32 v141, v81, v120
	v_fmac_f32_e32 v142, v81, v121
	v_fmac_f32_e32 v143, v81, v122
	v_fmac_f32_e32 v144, v81, v123
	v_fmac_f32_e32 v145, v81, v124
	v_fmac_f32_e32 v146, v81, v125
	v_fmac_f32_e32 v46, v82, v119
	v_fmac_f32_e32 v140, v82, v120
	v_fmac_f32_e32 v141, v82, v121
	v_fmac_f32_e32 v142, v82, v122
	v_fmac_f32_e32 v143, v82, v123
	v_fmac_f32_e32 v144, v82, v124
	v_fmac_f32_e32 v145, v82, v125
	s_waitcnt lgkmcnt(3)
	v_fmac_f32_e32 v146, v82, v126
	v_fmac_f32_e32 v46, v83, v120
	v_fmac_f32_e32 v140, v83, v121
	v_fmac_f32_e32 v141, v83, v122
	v_fmac_f32_e32 v142, v83, v123
	v_fmac_f32_e32 v143, v83, v124
	v_fmac_f32_e32 v144, v83, v125
	v_fmac_f32_e32 v145, v83, v126
	v_fmac_f32_e32 v146, v83, v127
	v_fmac_f32_e32 v46, v84, v121
	v_fmac_f32_e32 v140, v84, v122
	v_fmac_f32_e32 v141, v84, v123
	v_fmac_f32_e32 v142, v84, v124
	v_fmac_f32_e32 v143, v84, v125
	v_fmac_f32_e32 v144, v84, v126
	v_fmac_f32_e32 v145, v84, v127
	s_waitcnt lgkmcnt(2)
	v_fmac_f32_e32 v146, v84, v128
	v_fmac_f32_e32 v46, v85, v122
	v_fmac_f32_e32 v140, v85, v123
	v_fmac_f32_e32 v141, v85, v124
	v_fmac_f32_e32 v142, v85, v125
	v_fmac_f32_e32 v143, v85, v126
	v_fmac_f32_e32 v144, v85, v127
	v_fmac_f32_e32 v145, v85, v128
	v_fmac_f32_e32 v146, v85, v129
	v_fmac_f32_e32 v46, v86, v123
	v_fmac_f32_e32 v140, v86, v124
	v_fmac_f32_e32 v141, v86, v125
	v_fmac_f32_e32 v142, v86, v126
	v_fmac_f32_e32 v143, v86, v127
	v_fmac_f32_e32 v144, v86, v128
	v_fmac_f32_e32 v145, v86, v129
	s_waitcnt lgkmcnt(1)
	v_fmac_f32_e32 v146, v86, v130
	v_fmac_f32_e32 v46, v87, v124
	v_fmac_f32_e32 v140, v87, v125
	v_fmac_f32_e32 v141, v87, v126
	v_fmac_f32_e32 v142, v87, v127
	v_fmac_f32_e32 v143, v87, v128
	v_fmac_f32_e32 v144, v87, v129
	v_fmac_f32_e32 v145, v87, v130
	v_fmac_f32_e32 v146, v87, v131
	v_fmac_f32_e32 v46, v88, v125
	v_fmac_f32_e32 v140, v88, v126
	s_mov_b32 s2, 8
	s_mov_b64 s[10:11], 0
	s_and_b64 vcc, exec, vcc
	v_fmac_f32_e32 v141, v88, v127
	v_fmac_f32_e32 v142, v88, v128
	v_fmac_f32_e32 v143, v88, v129
	v_fmac_f32_e32 v144, v88, v130
	v_fmac_f32_e32 v145, v88, v131
	s_waitcnt lgkmcnt(0)
	v_fmac_f32_e32 v146, v88, v132
	v_fmac_f32_e32 v46, v89, v126
	v_fmac_f32_e32 v140, v89, v127
	v_add_u32_e32 v134, 0x800, v103
	v_add_u32_e32 v135, 0xc00, v103
	v_add_u32_e32 v136, 0x1000, v103
	v_add_u32_e32 v137, 0x1400, v103
	v_add_u32_e32 v138, 0x1800, v103
	v_add_u32_e32 v139, 0x1c00, v103
	v_fmac_f32_e32 v141, v89, v128
	v_fmac_f32_e32 v142, v89, v129
	v_fmac_f32_e32 v143, v89, v130
	v_fmac_f32_e32 v144, v89, v131
	v_fmac_f32_e32 v145, v89, v132
	v_fmac_f32_e32 v146, v89, v133
	ds_write2st64_b32 v103, v46, v140 offset0:248 offset1:252
	ds_write_b32 v134, v141 offset:63488
	ds_write_b32 v135, v142 offset:63488
	ds_write_b32 v136, v143 offset:63488
	ds_write_b32 v137, v144 offset:63488
	ds_write_b32 v138, v145 offset:63488
	ds_write_b32 v139, v146 offset:63488
	s_cbranch_vccz .LBB0_696
	v_add_u32_e32 v52, s17, v93
	v_add_u32_e32 v53, s19, v93
	v_add_u32_e32 v132, s21, v93
	v_add_u32_e32 v133, s23, v93
	s_waitcnt lgkmcnt(0)
	s_barrier
	ds_read_b128 v[104:107], v52 offset:63488
	ds_read_b128 v[108:111], v53 offset:63488
	ds_read_b128 v[112:115], v132 offset:63488
	ds_read_b128 v[116:119], v133 offset:63488
	s_waitcnt lgkmcnt(0)
	v_mov_b32_e32 v46, v105
	v_mov_b32_e32 v47, v106
	v_mov_b32_e32 v48, v104
	v_mov_b32_e32 v49, v107
	v_mov_b32_e32 v120, v109
	v_mov_b32_e32 v121, v110
	v_mov_b32_e32 v122, v108
	v_mov_b32_e32 v123, v111
	v_mov_b32_e32 v126, v113
	v_mov_b32_e32 v127, v114
	v_mov_b32_e32 v128, v112
	v_mov_b32_e32 v129, v115
	v_mov_b32_e32 v140, v117
	v_mov_b32_e32 v141, v118
	v_mov_b32_e32 v142, v116
	v_mov_b32_e32 v143, v119
	v_pk_add_f32 v[46:47], v[46:47], v[48:49]
	v_pk_add_f32 v[120:121], v[120:121], v[122:123]
	v_pk_add_f32 v[126:127], v[126:127], v[128:129]
	v_pk_add_f32 v[140:141], v[140:141], v[142:143]
	v_add_f32_e32 v46, v46, v47
	v_add_f32_e32 v120, v120, v121
	v_add_f32_e32 v126, v126, v127
	v_add_f32_e32 v140, v140, v141
	ds_bpermute_b32 v47, v94, v46
	ds_bpermute_b32 v121, v94, v120
	ds_bpermute_b32 v127, v94, v126
	ds_bpermute_b32 v141, v94, v140
	s_waitcnt lgkmcnt(0)
	v_add_f32_e32 v46, v46, v47
	v_add_f32_e32 v120, v120, v121
	v_add_f32_e32 v126, v126, v127
	v_add_f32_e32 v140, v140, v141
	ds_bpermute_b32 v47, v95, v46
	ds_bpermute_b32 v121, v95, v120
	ds_bpermute_b32 v127, v95, v126
	ds_bpermute_b32 v141, v95, v140
	s_waitcnt lgkmcnt(0)
	v_add_f32_e32 v46, v46, v47
	v_add_f32_e32 v120, v120, v121
	v_add_f32_e32 v126, v126, v127
	v_add_f32_e32 v140, v140, v141
	ds_bpermute_b32 v47, v96, v46
	ds_bpermute_b32 v121, v96, v120
	ds_bpermute_b32 v127, v96, v126
	ds_bpermute_b32 v141, v96, v140
	s_waitcnt lgkmcnt(0)
	v_add_f32_e32 v46, v46, v47
	v_add_f32_e32 v120, v120, v121
	v_add_f32_e32 v126, v126, v127
	v_add_f32_e32 v140, v140, v141
	ds_bpermute_b32 v47, v97, v46
	ds_bpermute_b32 v121, v97, v120
	ds_bpermute_b32 v127, v97, v126
	ds_bpermute_b32 v141, v97, v140
	s_waitcnt lgkmcnt(0)
	v_add_f32_e32 v46, v46, v47
	v_add_f32_e32 v120, v120, v121
	v_add_f32_e32 v126, v126, v127
	v_add_f32_e32 v140, v140, v141
	ds_bpermute_b32 v47, v98, v46
	ds_bpermute_b32 v121, v98, v120
	ds_bpermute_b32 v127, v98, v126
	ds_bpermute_b32 v141, v98, v140
	s_waitcnt lgkmcnt(0)
	v_add_f32_e32 v46, v46, v47
	v_add_f32_e32 v120, v120, v121
	v_add_f32_e32 v126, v126, v127
	v_add_f32_e32 v140, v140, v141
	ds_bpermute_b32 v47, v99, v46
	ds_bpermute_b32 v121, v99, v120
	ds_bpermute_b32 v127, v99, v126
	ds_bpermute_b32 v141, v99, v140
	s_waitcnt lgkmcnt(0)
	v_add_f32_e32 v46, v46, v47
	v_add_f32_e32 v120, v120, v121
	v_add_f32_e32 v126, v126, v127
	v_add_f32_e32 v140, v140, v141
	v_fmamk_f32 v105, v46, 0xbb800000, v105
	v_fmamk_f32 v104, v46, 0xbb800000, v104
	v_fmamk_f32 v107, v46, 0xbb800000, v107
	v_fmac_f32_e32 v106, 0xbb800000, v46
	v_fmamk_f32 v109, v120, 0xbb800000, v109
	v_fmamk_f32 v108, v120, 0xbb800000, v108
	v_fmamk_f32 v111, v120, 0xbb800000, v111
	v_fmac_f32_e32 v110, 0xbb800000, v120
	v_fmamk_f32 v113, v126, 0xbb800000, v113
	v_fmamk_f32 v112, v126, 0xbb800000, v112
	v_fmamk_f32 v115, v126, 0xbb800000, v115
	v_fmac_f32_e32 v114, 0xbb800000, v126
	v_fmamk_f32 v117, v140, 0xbb800000, v117
	v_fmamk_f32 v116, v140, 0xbb800000, v116
	v_fmamk_f32 v119, v140, 0xbb800000, v119
	v_fmac_f32_e32 v118, 0xbb800000, v140
	v_pk_mul_f32 v[46:47], v[106:107], v[106:107]
	v_pk_mul_f32 v[48:49], v[104:105], v[104:105]
	v_pk_mul_f32 v[120:121], v[110:111], v[110:111]
	v_pk_mul_f32 v[122:123], v[108:109], v[108:109]
	v_pk_mul_f32 v[126:127], v[114:115], v[114:115]
	v_pk_mul_f32 v[128:129], v[112:113], v[112:113]
	v_pk_mul_f32 v[140:141], v[118:119], v[118:119]
	v_pk_mul_f32 v[142:143], v[116:117], v[116:117]
	v_pk_mov_b32 v[50:51], v[48:49], v[46:47] op_sel:[1,0]
	v_pk_mov_b32 v[124:125], v[122:123], v[120:121] op_sel:[1,0]
	v_pk_mov_b32 v[130:131], v[128:129], v[126:127] op_sel:[1,0]
	v_pk_mov_b32 v[144:145], v[142:143], v[140:141] op_sel:[1,0]
	v_mov_b32_e32 v49, v47
	v_mov_b32_e32 v123, v121
	v_mov_b32_e32 v129, v127
	v_mov_b32_e32 v143, v141
	v_pk_add_f32 v[46:47], v[50:51], v[48:49]
	v_pk_add_f32 v[120:121], v[124:125], v[122:123]
	v_pk_add_f32 v[126:127], v[130:131], v[128:129]
	v_pk_add_f32 v[140:141], v[144:145], v[142:143]
	v_add_f32_e32 v46, v46, v47
	v_add_f32_e32 v120, v120, v121
	v_add_f32_e32 v126, v126, v127
	v_add_f32_e32 v140, v140, v141
	ds_bpermute_b32 v47, v94, v46
	ds_bpermute_b32 v121, v94, v120
	ds_bpermute_b32 v127, v94, v126
	ds_bpermute_b32 v141, v94, v140
	s_waitcnt lgkmcnt(0)
	v_add_f32_e32 v46, v46, v47
	v_add_f32_e32 v120, v120, v121
	v_add_f32_e32 v126, v126, v127
	v_add_f32_e32 v140, v140, v141
	ds_bpermute_b32 v47, v95, v46
	ds_bpermute_b32 v121, v95, v120
	ds_bpermute_b32 v127, v95, v126
	ds_bpermute_b32 v141, v95, v140
	s_waitcnt lgkmcnt(0)
	v_add_f32_e32 v46, v46, v47
	v_add_f32_e32 v120, v120, v121
	v_add_f32_e32 v126, v126, v127
	v_add_f32_e32 v140, v140, v141
	ds_bpermute_b32 v47, v96, v46
	ds_bpermute_b32 v121, v96, v120
	ds_bpermute_b32 v127, v96, v126
	ds_bpermute_b32 v141, v96, v140
	s_waitcnt lgkmcnt(0)
	v_add_f32_e32 v46, v46, v47
	v_add_f32_e32 v120, v120, v121
	v_add_f32_e32 v126, v126, v127
	v_add_f32_e32 v140, v140, v141
	ds_bpermute_b32 v47, v97, v46
	ds_bpermute_b32 v121, v97, v120
	ds_bpermute_b32 v127, v97, v126
	ds_bpermute_b32 v141, v97, v140
	s_waitcnt lgkmcnt(0)
	v_add_f32_e32 v46, v46, v47
	v_add_f32_e32 v120, v120, v121
	v_add_f32_e32 v126, v126, v127
	v_add_f32_e32 v140, v140, v141
	ds_bpermute_b32 v47, v98, v46
	ds_bpermute_b32 v121, v98, v120
	ds_bpermute_b32 v127, v98, v126
	ds_bpermute_b32 v141, v98, v140
	s_waitcnt lgkmcnt(0)
	v_add_f32_e32 v46, v46, v47
	v_add_f32_e32 v120, v120, v121
	v_add_f32_e32 v126, v126, v127
	v_add_f32_e32 v140, v140, v141
	ds_bpermute_b32 v47, v99, v46
	ds_bpermute_b32 v121, v99, v120
	ds_bpermute_b32 v127, v99, v126
	ds_bpermute_b32 v141, v99, v140
	s_waitcnt lgkmcnt(0)
	v_add_f32_e32 v46, v46, v47
	v_add_f32_e32 v120, v120, v121
	v_add_f32_e32 v126, v126, v127
	v_add_f32_e32 v140, v140, v141
	v_fmamk_f32 v46, v46, 0x3b800000, v247
	v_fmamk_f32 v120, v120, 0x3b800000, v247
	v_fmamk_f32 v126, v126, 0x3b800000, v247
	v_fmamk_f32 v140, v140, 0x3b800000, v247
	v_cmp_gt_f32_e32 vcc, s12, v46
	v_mul_f32_e32 v47, 0x4f800000, v46
	s_nop 0
	v_cndmask_b32_e32 v46, v46, v47, vcc
	v_sqrt_f32_e32 v47, v46
	s_nop 0
	v_add_u32_e32 v146, -1, v47
	v_fma_f32 v147, -v146, v47, v46
	v_cmp_ge_f32_e64 s[10:11], 0, v147
	v_add_u32_e32 v147, 1, v47
	s_nop 0
	v_cndmask_b32_e64 v146, v47, v146, s[10:11]
	v_fma_f32 v47, -v147, v47, v46
	v_cmp_lt_f32_e64 s[10:11], 0, v47
	s_nop 1
	v_cndmask_b32_e64 v47, v146, v147, s[10:11]
	v_mul_f32_e32 v146, 0x37800000, v47
	v_cndmask_b32_e32 v47, v47, v146, vcc
	v_cmp_class_f32_e32 vcc, v46, v246
	s_nop 1
	v_cndmask_b32_e32 v46, v47, v46, vcc
	v_div_scale_f32 v47, s[2:3], v46, v46, 1.0
	v_rcp_f32_e32 v146, v47
	s_add_i32 s2, s24, s16
	s_ashr_i32 s3, s2, 31
	s_lshl_b64 s[2:3], s[2:3], 11
	v_fma_f32 v147, -v47, v146, 1.0
	v_fmac_f32_e32 v146, v147, v146
	v_div_scale_f32 v147, vcc, 1.0, v46, 1.0
	v_mul_f32_e32 v103, v147, v146
	v_fma_f32 v133, -v47, v103, v147
	v_fmac_f32_e32 v103, v133, v146
	v_fma_f32 v47, -v47, v103, v147
	v_div_fmas_f32 v47, v47, v146, v103
	v_div_fixup_f32 v46, v47, v46, 1.0
	v_pk_mul_f32 v[104:105], v[104:105], v[46:47] op_sel_hi:[1,0]
	v_pk_mul_f32 v[106:107], v[106:107], v[46:47] op_sel_hi:[1,0]
	v_pk_fma_f32 v[104:105], v[38:39], v[104:105], v[42:43]
	v_pk_fma_f32 v[106:107], v[40:41], v[106:107], v[44:45]
	v_mul_f32_e32 v46, 0xbfb8aa3b, v104
	v_mul_f32_e32 v47, 0xbfb8aa3b, v105
	v_exp_f32_e32 v46, v46
	v_exp_f32_e32 v47, v47
	v_add_f32_e32 v46, 1.0, v46
	v_add_f32_e32 v47, 1.0, v47
	v_rcp_f32_e32 v46, v46
	v_rcp_f32_e32 v47, v47
	s_nop 0
	v_pk_mul_f32 v[104:105], v[104:105], v[46:47]
	v_mul_f32_e32 v46, 0xbfb8aa3b, v106
	v_mul_f32_e32 v47, 0xbfb8aa3b, v107
	v_exp_f32_e32 v46, v46
	v_exp_f32_e32 v47, v47
	v_cvt_pk_bf16_f32 v104, v104, v105
	v_add_f32_e32 v46, 1.0, v46
	v_add_f32_e32 v47, 1.0, v47
	v_rcp_f32_e32 v46, v46
	v_rcp_f32_e32 v47, v47
	s_nop 0
	v_pk_mul_f32 v[106:107], v[106:107], v[46:47]
	s_nop 0
	v_cvt_pk_bf16_f32 v105, v106, v107
	v_lshl_add_u64 v[106:107], v[54:55], 0, s[2:3]
	global_store_dwordx2 v[106:107], v[104:105], off offset:1536
	v_cmp_gt_f32_e32 vcc, s12, v120
	v_mul_f32_e32 v121, 0x4f800000, v120
	s_nop 0
	v_cndmask_b32_e32 v120, v120, v121, vcc
	v_sqrt_f32_e32 v121, v120
	s_nop 0
	v_add_u32_e32 v146, -1, v121
	v_fma_f32 v147, -v146, v121, v120
	v_cmp_ge_f32_e64 s[10:11], 0, v147
	v_add_u32_e32 v147, 1, v121
	s_nop 0
	v_cndmask_b32_e64 v146, v121, v146, s[10:11]
	v_fma_f32 v121, -v147, v121, v120
	v_cmp_lt_f32_e64 s[10:11], 0, v121
	s_nop 1
	v_cndmask_b32_e64 v121, v146, v147, s[10:11]
	v_mul_f32_e32 v146, 0x37800000, v121
	v_cndmask_b32_e32 v121, v121, v146, vcc
	v_cmp_class_f32_e32 vcc, v120, v246
	s_nop 1
	v_cndmask_b32_e32 v120, v121, v120, vcc
	v_div_scale_f32 v121, s[2:3], v120, v120, 1.0
	v_rcp_f32_e32 v146, v121
	s_add_i32 s2, s24, s18
	s_ashr_i32 s3, s2, 31
	s_lshl_b64 s[2:3], s[2:3], 11
	v_fma_f32 v147, -v121, v146, 1.0
	v_fmac_f32_e32 v146, v147, v146
	v_div_scale_f32 v147, vcc, 1.0, v120, 1.0
	v_mul_f32_e32 v103, v147, v146
	v_fma_f32 v133, -v121, v103, v147
	v_fmac_f32_e32 v103, v133, v146
	v_fma_f32 v121, -v121, v103, v147
	v_div_fmas_f32 v121, v121, v146, v103
	v_div_fixup_f32 v120, v121, v120, 1.0
	v_pk_mul_f32 v[108:109], v[108:109], v[120:121] op_sel_hi:[1,0]
	v_pk_mul_f32 v[110:111], v[110:111], v[120:121] op_sel_hi:[1,0]
	v_pk_fma_f32 v[108:109], v[38:39], v[108:109], v[42:43]
	v_pk_fma_f32 v[110:111], v[40:41], v[110:111], v[44:45]
	v_mul_f32_e32 v120, 0xbfb8aa3b, v108
	v_mul_f32_e32 v121, 0xbfb8aa3b, v109
	v_exp_f32_e32 v120, v120
	v_exp_f32_e32 v121, v121
	v_add_f32_e32 v120, 1.0, v120
	v_add_f32_e32 v121, 1.0, v121
	v_rcp_f32_e32 v120, v120
	v_rcp_f32_e32 v121, v121
	s_nop 0
	v_pk_mul_f32 v[108:109], v[108:109], v[120:121]
	v_mul_f32_e32 v120, 0xbfb8aa3b, v110
	v_mul_f32_e32 v121, 0xbfb8aa3b, v111
	v_exp_f32_e32 v120, v120
	v_exp_f32_e32 v121, v121
	v_cvt_pk_bf16_f32 v108, v108, v109
	v_add_f32_e32 v120, 1.0, v120
	v_add_f32_e32 v121, 1.0, v121
	v_rcp_f32_e32 v120, v120
	v_rcp_f32_e32 v121, v121
	s_nop 0
	v_pk_mul_f32 v[110:111], v[110:111], v[120:121]
	s_nop 0
	v_cvt_pk_bf16_f32 v109, v110, v111
	v_lshl_add_u64 v[110:111], v[54:55], 0, s[2:3]
	global_store_dwordx2 v[110:111], v[108:109], off offset:1536
	v_cmp_gt_f32_e32 vcc, s12, v126
	v_mul_f32_e32 v127, 0x4f800000, v126
	s_nop 0
	v_cndmask_b32_e32 v126, v126, v127, vcc
	v_sqrt_f32_e32 v127, v126
	s_nop 0
	v_add_u32_e32 v146, -1, v127
	v_fma_f32 v147, -v146, v127, v126
	v_cmp_ge_f32_e64 s[10:11], 0, v147
	v_add_u32_e32 v147, 1, v127
	s_nop 0
	v_cndmask_b32_e64 v146, v127, v146, s[10:11]
	v_fma_f32 v127, -v147, v127, v126
	v_cmp_lt_f32_e64 s[10:11], 0, v127
	s_nop 1
	v_cndmask_b32_e64 v127, v146, v147, s[10:11]
	v_mul_f32_e32 v146, 0x37800000, v127
	v_cndmask_b32_e32 v127, v127, v146, vcc
	v_cmp_class_f32_e32 vcc, v126, v246
	s_nop 1
	v_cndmask_b32_e32 v126, v127, v126, vcc
	v_div_scale_f32 v127, s[2:3], v126, v126, 1.0
	v_rcp_f32_e32 v146, v127
	s_add_i32 s2, s24, s20
	s_ashr_i32 s3, s2, 31
	s_lshl_b64 s[2:3], s[2:3], 11
	v_fma_f32 v147, -v127, v146, 1.0
	v_fmac_f32_e32 v146, v147, v146
	v_div_scale_f32 v147, vcc, 1.0, v126, 1.0
	v_mul_f32_e32 v103, v147, v146
	v_fma_f32 v133, -v127, v103, v147
	v_fmac_f32_e32 v103, v133, v146
	v_fma_f32 v127, -v127, v103, v147
	v_div_fmas_f32 v127, v127, v146, v103
	v_div_fixup_f32 v126, v127, v126, 1.0
	v_pk_mul_f32 v[112:113], v[112:113], v[126:127] op_sel_hi:[1,0]
	v_pk_mul_f32 v[114:115], v[114:115], v[126:127] op_sel_hi:[1,0]
	v_pk_fma_f32 v[112:113], v[38:39], v[112:113], v[42:43]
	v_pk_fma_f32 v[114:115], v[40:41], v[114:115], v[44:45]
	v_mul_f32_e32 v126, 0xbfb8aa3b, v112
	v_mul_f32_e32 v127, 0xbfb8aa3b, v113
	v_exp_f32_e32 v126, v126
	v_exp_f32_e32 v127, v127
	v_add_f32_e32 v126, 1.0, v126
	v_add_f32_e32 v127, 1.0, v127
	v_rcp_f32_e32 v126, v126
	v_rcp_f32_e32 v127, v127
	s_nop 0
	v_pk_mul_f32 v[112:113], v[112:113], v[126:127]
	v_mul_f32_e32 v126, 0xbfb8aa3b, v114
	v_mul_f32_e32 v127, 0xbfb8aa3b, v115
	v_exp_f32_e32 v126, v126
	v_exp_f32_e32 v127, v127
	v_cvt_pk_bf16_f32 v112, v112, v113
	v_add_f32_e32 v126, 1.0, v126
	v_add_f32_e32 v127, 1.0, v127
	v_rcp_f32_e32 v126, v126
	v_rcp_f32_e32 v127, v127
	s_nop 0
	v_pk_mul_f32 v[114:115], v[114:115], v[126:127]
	s_nop 0
	v_cvt_pk_bf16_f32 v113, v114, v115
	v_lshl_add_u64 v[114:115], v[54:55], 0, s[2:3]
	global_store_dwordx2 v[114:115], v[112:113], off offset:1536
	v_cmp_gt_f32_e32 vcc, s12, v140
	v_mul_f32_e32 v141, 0x4f800000, v140
	s_nop 0
	v_cndmask_b32_e32 v140, v140, v141, vcc
	v_sqrt_f32_e32 v141, v140
	s_nop 0
	v_add_u32_e32 v146, -1, v141
	v_fma_f32 v147, -v146, v141, v140
	v_cmp_ge_f32_e64 s[10:11], 0, v147
	v_add_u32_e32 v147, 1, v141
	s_nop 0
	v_cndmask_b32_e64 v146, v141, v146, s[10:11]
	v_fma_f32 v141, -v147, v141, v140
	v_cmp_lt_f32_e64 s[10:11], 0, v141
	s_nop 1
	v_cndmask_b32_e64 v141, v146, v147, s[10:11]
	v_mul_f32_e32 v146, 0x37800000, v141
	v_cndmask_b32_e32 v141, v141, v146, vcc
	v_cmp_class_f32_e32 vcc, v140, v246
	s_nop 1
	v_cndmask_b32_e32 v140, v141, v140, vcc
	v_div_scale_f32 v141, s[2:3], v140, v140, 1.0
	v_rcp_f32_e32 v146, v141
	s_add_i32 s2, s24, s22
	s_ashr_i32 s3, s2, 31
	s_lshl_b64 s[2:3], s[2:3], 11
	v_fma_f32 v147, -v141, v146, 1.0
	v_fmac_f32_e32 v146, v147, v146
	v_div_scale_f32 v147, vcc, 1.0, v140, 1.0
	v_mul_f32_e32 v103, v147, v146
	v_fma_f32 v133, -v141, v103, v147
	v_fmac_f32_e32 v103, v133, v146
	v_fma_f32 v141, -v141, v103, v147
	v_div_fmas_f32 v141, v141, v146, v103
	v_div_fixup_f32 v140, v141, v140, 1.0
	v_pk_mul_f32 v[116:117], v[116:117], v[140:141] op_sel_hi:[1,0]
	v_pk_mul_f32 v[118:119], v[118:119], v[140:141] op_sel_hi:[1,0]
	v_pk_fma_f32 v[116:117], v[38:39], v[116:117], v[42:43]
	v_pk_fma_f32 v[118:119], v[40:41], v[118:119], v[44:45]
	v_mul_f32_e32 v140, 0xbfb8aa3b, v116
	v_mul_f32_e32 v141, 0xbfb8aa3b, v117
	v_exp_f32_e32 v140, v140
	v_exp_f32_e32 v141, v141
	s_cmp_eq_u32 s15, s77
	v_add_f32_e32 v140, 1.0, v140
	v_add_f32_e32 v141, 1.0, v141
	v_rcp_f32_e32 v140, v140
	v_rcp_f32_e32 v141, v141
	s_nop 0
	v_pk_mul_f32 v[116:117], v[116:117], v[140:141]
	v_mul_f32_e32 v140, 0xbfb8aa3b, v118
	v_mul_f32_e32 v141, 0xbfb8aa3b, v119
	v_exp_f32_e32 v140, v140
	v_exp_f32_e32 v141, v141
	v_cvt_pk_bf16_f32 v116, v116, v117
	v_add_f32_e32 v140, 1.0, v140
	v_add_f32_e32 v141, 1.0, v141
	v_rcp_f32_e32 v140, v140
	v_rcp_f32_e32 v141, v141
	s_nop 0
	v_pk_mul_f32 v[118:119], v[118:119], v[140:141]
	s_nop 0
	v_cvt_pk_bf16_f32 v117, v118, v119
	v_lshl_add_u64 v[118:119], v[54:55], 0, s[2:3]
	global_store_dwordx2 v[118:119], v[116:117], off offset:1536
	s_barrier
	s_cbranch_scc0 .LBB0_677
	s_mov_b64 s[0:1], 0
